# v53: v37 + conv LayerNorm store addresses by strength reduction (first address, then +4096 per token)
# speedup vs baseline: 1.0004x; 1.0004x over previous
; __device__ __forceinline__ void conv_phase(LAS unsigned char* lds, const bf16_t* P, const float* cw, const float* cb, const float* ng, const float* nb, bf16_t* CAT, int bid, int G, const int tid) {
;     ...
;             for (int i = 0; i < 46; ++i) {
;                 const float z = zs[(tb * 16 + i) * 128 + c];
; #pragma unroll
;                 for (int o = 0; o < 16; ++o) { const int j = i - o; if (j >= 0 && j <= 30) acc[o] += wj[j] * z; }
;             }
; #pragma unroll
;             for (int o = 0; o < 16; ++o) co[(tb * 16 + o) * 128 + c] = acc[o];
.Lconv_wok:
	v_or_b32_e32 v31, s30, v39
	v_lshlrev_b32_e32 v176, 2, v31
	ds_read2st64_b32 v[90:91], v40 offset0:12 offset1:14
	ds_read2st64_b32 v[94:95], v40 offset0:16 offset1:18
	ds_read2st64_b32 v[98:99], v40 offset0:20 offset1:22
	ds_read2st64_b32 v[102:103], v40 offset0:24 offset1:26
	ds_read2st64_b32 v[108:109], v40 offset0:28 offset1:30
	s_and_b32 s31, s34, 0xffffffc0
	s_mov_b32 s34, s15
	s_mov_b32 s35, s17
	v_mov_b32_e32 v31, v223
	ds_read2st64_b32 v[74:75], v40 offset1:2
	v_mov_b32_e32 v33, v225
	ds_read2st64_b32 v[86:87], v40 offset0:4 offset1:6
	s_lshl_b32 s26, s30, 2
	s_andn2_b64 vcc, exec, s[20:21]
	s_waitcnt lgkmcnt(0)
	v_fma_f32 v74, v194, v74, v33
	v_fmac_f32_e32 v74, v195, v75
	v_fma_f32 v75, v194, v75, v33
	v_fmac_f32_e32 v74, v196, v86
	v_fmac_f32_e32 v75, v195, v86
	v_fma_f32 v83, v194, v86, v33
	v_fmac_f32_e32 v74, v197, v87
	v_fmac_f32_e32 v75, v196, v87
	v_fmac_f32_e32 v83, v195, v87
	v_fma_f32 v84, v194, v87, v33
	ds_read2st64_b32 v[86:87], v40 offset0:8 offset1:10
	v_fma_f32 v106, v194, v108, v33
	v_fmac_f32_e32 v106, v195, v109
	s_waitcnt lgkmcnt(0)
	v_fmac_f32_e32 v74, v198, v86
	v_fmac_f32_e32 v75, v197, v86
	v_fmac_f32_e32 v83, v196, v86
	v_fmac_f32_e32 v84, v195, v86
	v_fma_f32 v86, v194, v86, v33
	v_fmac_f32_e32 v74, v199, v87
	v_fmac_f32_e32 v75, v198, v87
	v_fmac_f32_e32 v83, v197, v87
	v_fmac_f32_e32 v84, v196, v87
	v_fmac_f32_e32 v86, v195, v87
	v_fma_f32 v87, v194, v87, v33
	v_fmac_f32_e32 v74, v200, v90
	v_fmac_f32_e32 v75, v199, v90
	v_fmac_f32_e32 v83, v198, v90
	v_fmac_f32_e32 v84, v197, v90
	v_fmac_f32_e32 v86, v196, v90
	v_fmac_f32_e32 v87, v195, v90
	v_fma_f32 v90, v194, v90, v33
	v_fmac_f32_e32 v74, v201, v91
	v_fmac_f32_e32 v75, v200, v91
	v_fmac_f32_e32 v83, v199, v91
	v_fmac_f32_e32 v84, v198, v91
	v_fmac_f32_e32 v86, v197, v91
	v_fmac_f32_e32 v87, v196, v91
	v_fmac_f32_e32 v90, v195, v91
	v_fma_f32 v91, v194, v91, v33
	v_fmac_f32_e32 v74, v202, v94
	v_fmac_f32_e32 v75, v201, v94
	v_fmac_f32_e32 v83, v200, v94
	v_fmac_f32_e32 v84, v199, v94
	v_fmac_f32_e32 v86, v198, v94
	v_fmac_f32_e32 v87, v197, v94
	v_fmac_f32_e32 v90, v196, v94
	v_fmac_f32_e32 v91, v195, v94
	v_fma_f32 v94, v194, v94, v33
	v_fmac_f32_e32 v74, v203, v95
	v_fmac_f32_e32 v75, v202, v95
	v_fmac_f32_e32 v83, v201, v95
	v_fmac_f32_e32 v84, v200, v95
	v_fmac_f32_e32 v86, v199, v95
	v_fmac_f32_e32 v87, v198, v95
	v_fmac_f32_e32 v90, v197, v95
	v_fmac_f32_e32 v91, v196, v95
	v_fmac_f32_e32 v94, v195, v95
	v_fma_f32 v95, v194, v95, v33
	v_fmac_f32_e32 v74, v204, v98
	v_fmac_f32_e32 v75, v203, v98
	v_fmac_f32_e32 v83, v202, v98
	v_fmac_f32_e32 v84, v201, v98
	v_fmac_f32_e32 v86, v200, v98
	v_fmac_f32_e32 v87, v199, v98
	v_fmac_f32_e32 v90, v198, v98
	v_fmac_f32_e32 v91, v197, v98
	v_fmac_f32_e32 v94, v196, v98
	v_fmac_f32_e32 v95, v195, v98
	v_fma_f32 v98, v194, v98, v33
	v_fmac_f32_e32 v74, v205, v99
	v_fmac_f32_e32 v75, v204, v99
	v_fmac_f32_e32 v83, v203, v99
	v_fmac_f32_e32 v84, v202, v99
	v_fmac_f32_e32 v86, v201, v99
	v_fmac_f32_e32 v87, v200, v99
	v_fmac_f32_e32 v90, v199, v99
	v_fmac_f32_e32 v91, v198, v99
	v_fmac_f32_e32 v94, v197, v99
	v_fmac_f32_e32 v95, v196, v99
	v_fmac_f32_e32 v98, v195, v99
	v_fma_f32 v99, v194, v99, v33
	v_fmac_f32_e32 v74, v206, v102
	v_fmac_f32_e32 v75, v205, v102
	v_fmac_f32_e32 v83, v204, v102
	v_fmac_f32_e32 v84, v203, v102
	v_fmac_f32_e32 v86, v202, v102
	v_fmac_f32_e32 v87, v201, v102
	v_fmac_f32_e32 v90, v200, v102
	v_fmac_f32_e32 v91, v199, v102
	v_fmac_f32_e32 v94, v198, v102
	v_fmac_f32_e32 v95, v197, v102
	v_fmac_f32_e32 v98, v196, v102
	v_fmac_f32_e32 v99, v195, v102
	v_fma_f32 v102, v194, v102, v33
	v_fmac_f32_e32 v74, v207, v103
	v_fmac_f32_e32 v75, v206, v103
	v_fmac_f32_e32 v83, v205, v103
	v_fmac_f32_e32 v84, v204, v103
	v_fmac_f32_e32 v86, v203, v103
	v_fmac_f32_e32 v87, v202, v103
	v_fmac_f32_e32 v90, v201, v103
	v_fmac_f32_e32 v91, v200, v103
	v_fmac_f32_e32 v94, v199, v103
	v_fmac_f32_e32 v95, v198, v103
	v_fmac_f32_e32 v98, v197, v103
	v_fmac_f32_e32 v99, v196, v103
	v_fmac_f32_e32 v102, v195, v103
	v_fma_f32 v103, v194, v103, v33
	v_fmac_f32_e32 v74, v208, v108
	v_fmac_f32_e32 v75, v207, v108
	v_fmac_f32_e32 v83, v206, v108
	v_fmac_f32_e32 v84, v205, v108
	v_fmac_f32_e32 v86, v204, v108
	v_fmac_f32_e32 v87, v203, v108
	v_fmac_f32_e32 v90, v202, v108
	v_fmac_f32_e32 v91, v201, v108
	v_fmac_f32_e32 v94, v200, v108
	v_fmac_f32_e32 v95, v199, v108
	v_fmac_f32_e32 v98, v198, v108
	v_fmac_f32_e32 v99, v197, v108
	v_fmac_f32_e32 v102, v196, v108
	v_fmac_f32_e32 v103, v195, v108
	v_fmac_f32_e32 v74, v209, v109
	v_fmac_f32_e32 v75, v208, v109
	v_fmac_f32_e32 v83, v207, v109
	v_fmac_f32_e32 v84, v206, v109
	v_fmac_f32_e32 v86, v205, v109
	v_fmac_f32_e32 v87, v204, v109
	v_fmac_f32_e32 v90, v203, v109
	v_fmac_f32_e32 v91, v202, v109
	v_fmac_f32_e32 v94, v201, v109
	v_fmac_f32_e32 v95, v200, v109
	v_fmac_f32_e32 v98, v199, v109
	v_fmac_f32_e32 v99, v198, v109
	v_fmac_f32_e32 v102, v197, v109
	v_fmac_f32_e32 v103, v196, v109
	v_fmac_f32_e32 v33, v194, v109
	ds_read2st64_b32 v[108:109], v40 offset0:32 offset1:34
	s_waitcnt lgkmcnt(0)
	v_fmac_f32_e32 v33, v195, v108
	v_fmac_f32_e32 v106, v196, v108
	v_fmac_f32_e32 v33, v196, v109
	ds_read2st64_b32 v[104:105], v40 offset0:36 offset1:38
	v_fmac_f32_e32 v103, v197, v108
	v_fmac_f32_e32 v106, v197, v109
	v_fmac_f32_e32 v102, v198, v108
	v_fmac_f32_e32 v103, v198, v109
	s_waitcnt lgkmcnt(0)
	v_fmac_f32_e32 v33, v197, v104
	v_fmac_f32_e32 v106, v198, v104
	v_fmac_f32_e32 v33, v198, v105
	ds_read2st64_b32 v[100:101], v40 offset0:40 offset1:42
	v_fmac_f32_e32 v99, v199, v108
	v_fmac_f32_e32 v102, v199, v109
	v_fmac_f32_e32 v103, v199, v104
	v_fmac_f32_e32 v106, v199, v105
	s_waitcnt lgkmcnt(0)
; __device__ __forceinline__ void conv_phase(LAS unsigned char* lds, const bf16_t* P, const float* cw, const float* cb, const float* ng, const float* nb, bf16_t* CAT, int bid, int G, const int tid) {
;     ...
;             for (int i = 0; i < 46; ++i) {
;                 const float z = zs[(tb * 16 + i) * 128 + c];
; #pragma unroll
;                 for (int o = 0; o < 16; ++o) { const int j = i - o; if (j >= 0 && j <= 30) acc[o] += wj[j] * z; }
;             }
; #pragma unroll
;             for (int o = 0; o < 16; ++o) co[(tb * 16 + o) * 128 + c] = acc[o];
	v_fmac_f32_e32 v33, v199, v100
	v_fmac_f32_e32 v98, v200, v108
	v_fmac_f32_e32 v99, v200, v109
	v_fmac_f32_e32 v102, v200, v104
	v_fmac_f32_e32 v103, v200, v105
	v_fmac_f32_e32 v106, v200, v100
	v_fmac_f32_e32 v33, v200, v101
	ds_read2st64_b32 v[96:97], v40 offset0:44 offset1:46
	v_fmac_f32_e32 v95, v201, v108
	v_fmac_f32_e32 v98, v201, v109
	v_fmac_f32_e32 v99, v201, v104
	v_fmac_f32_e32 v102, v201, v105
	v_fmac_f32_e32 v103, v201, v100
	v_fmac_f32_e32 v106, v201, v101
	s_waitcnt lgkmcnt(0)
	v_fmac_f32_e32 v33, v201, v96
	v_fmac_f32_e32 v94, v202, v108
	v_fmac_f32_e32 v95, v202, v109
	v_fmac_f32_e32 v98, v202, v104
	v_fmac_f32_e32 v99, v202, v105
	v_fmac_f32_e32 v102, v202, v100
	v_fmac_f32_e32 v103, v202, v101
	v_fmac_f32_e32 v106, v202, v96
	v_fmac_f32_e32 v33, v202, v97
	ds_read2st64_b32 v[92:93], v40 offset0:48 offset1:50
	v_fmac_f32_e32 v74, v210, v108
	v_fmac_f32_e32 v75, v209, v108
	v_fmac_f32_e32 v83, v208, v108
	v_fmac_f32_e32 v84, v207, v108
	v_fmac_f32_e32 v86, v206, v108
	v_fmac_f32_e32 v87, v205, v108
	v_fmac_f32_e32 v90, v204, v108
	v_fmac_f32_e32 v91, v203, v108
	v_fmac_f32_e32 v74, v211, v109
	v_fmac_f32_e32 v75, v210, v109
	v_fmac_f32_e32 v83, v209, v109
	v_fmac_f32_e32 v84, v208, v109
	v_fmac_f32_e32 v86, v207, v109
	v_fmac_f32_e32 v87, v206, v109
	v_fmac_f32_e32 v90, v205, v109
	v_fmac_f32_e32 v91, v204, v109
	v_fmac_f32_e32 v94, v203, v109
	v_fmac_f32_e32 v74, v212, v104
	v_fmac_f32_e32 v75, v211, v104
	v_fmac_f32_e32 v83, v210, v104
	v_fmac_f32_e32 v84, v209, v104
	v_fmac_f32_e32 v86, v208, v104
	v_fmac_f32_e32 v87, v207, v104
	v_fmac_f32_e32 v90, v206, v104
	v_fmac_f32_e32 v91, v205, v104
	v_fmac_f32_e32 v94, v204, v104
	v_fmac_f32_e32 v95, v203, v104
	v_fmac_f32_e32 v74, v213, v105
	v_fmac_f32_e32 v75, v212, v105
	v_fmac_f32_e32 v83, v211, v105
	v_fmac_f32_e32 v84, v210, v105
	v_fmac_f32_e32 v86, v209, v105
	v_fmac_f32_e32 v87, v208, v105
	v_fmac_f32_e32 v90, v207, v105
	v_fmac_f32_e32 v91, v206, v105
	v_fmac_f32_e32 v94, v205, v105
	v_fmac_f32_e32 v95, v204, v105
	v_fmac_f32_e32 v98, v203, v105
	v_fmac_f32_e32 v74, v214, v100
	v_fmac_f32_e32 v75, v213, v100
	v_fmac_f32_e32 v83, v212, v100
	v_fmac_f32_e32 v84, v211, v100
	v_fmac_f32_e32 v86, v210, v100
	v_fmac_f32_e32 v87, v209, v100
	v_fmac_f32_e32 v90, v208, v100
	v_fmac_f32_e32 v91, v207, v100
	v_fmac_f32_e32 v94, v206, v100
	v_fmac_f32_e32 v95, v205, v100
	v_fmac_f32_e32 v98, v204, v100
	v_fmac_f32_e32 v99, v203, v100
	v_fmac_f32_e32 v102, v203, v101
	v_fmac_f32_e32 v103, v203, v96
	v_fmac_f32_e32 v106, v203, v97
	s_waitcnt lgkmcnt(0)
	v_fmac_f32_e32 v33, v203, v92
	v_fmac_f32_e32 v74, v215, v101
	v_fmac_f32_e32 v75, v214, v101
	v_fmac_f32_e32 v83, v213, v101
	v_fmac_f32_e32 v84, v212, v101
	v_fmac_f32_e32 v86, v211, v101
	v_fmac_f32_e32 v87, v210, v101
	v_fmac_f32_e32 v90, v209, v101
	v_fmac_f32_e32 v91, v208, v101
	v_fmac_f32_e32 v94, v207, v101
	v_fmac_f32_e32 v95, v206, v101
	v_fmac_f32_e32 v98, v205, v101
	v_fmac_f32_e32 v99, v204, v101
	v_fmac_f32_e32 v102, v204, v96
	v_fmac_f32_e32 v103, v204, v97
	v_fmac_f32_e32 v106, v204, v92
	v_fmac_f32_e32 v33, v204, v93
	ds_read2st64_b32 v[88:89], v40 offset0:52 offset1:54
	v_fmac_f32_e32 v74, v216, v96
	v_fmac_f32_e32 v75, v215, v96
	v_fmac_f32_e32 v83, v214, v96
	v_fmac_f32_e32 v84, v213, v96
	v_fmac_f32_e32 v86, v212, v96
	v_fmac_f32_e32 v87, v211, v96
	v_fmac_f32_e32 v90, v210, v96
	v_fmac_f32_e32 v91, v209, v96
	v_fmac_f32_e32 v94, v208, v96
	v_fmac_f32_e32 v95, v207, v96
	v_fmac_f32_e32 v98, v206, v96
	v_fmac_f32_e32 v99, v205, v96
	v_fmac_f32_e32 v74, v217, v97
	v_fmac_f32_e32 v75, v216, v97
	v_fmac_f32_e32 v83, v215, v97
	v_fmac_f32_e32 v84, v214, v97
	v_fmac_f32_e32 v86, v213, v97
	v_fmac_f32_e32 v87, v212, v97
	v_fmac_f32_e32 v90, v211, v97
	v_fmac_f32_e32 v91, v210, v97
	v_fmac_f32_e32 v94, v209, v97
	v_fmac_f32_e32 v95, v208, v97
	v_fmac_f32_e32 v98, v207, v97
	v_fmac_f32_e32 v99, v206, v97
	v_fmac_f32_e32 v102, v205, v97
	v_fmac_f32_e32 v74, v218, v92
	v_fmac_f32_e32 v75, v217, v92
	v_fmac_f32_e32 v83, v216, v92
	v_fmac_f32_e32 v84, v215, v92
	v_fmac_f32_e32 v86, v214, v92
	v_fmac_f32_e32 v87, v213, v92
	v_fmac_f32_e32 v90, v212, v92
	v_fmac_f32_e32 v91, v211, v92
	v_fmac_f32_e32 v94, v210, v92
	v_fmac_f32_e32 v95, v209, v92
	v_fmac_f32_e32 v98, v208, v92
	v_fmac_f32_e32 v99, v207, v92
	v_fmac_f32_e32 v102, v206, v92
	v_fmac_f32_e32 v103, v205, v92
	v_fmac_f32_e32 v74, v219, v93
	v_fmac_f32_e32 v75, v218, v93
	v_fmac_f32_e32 v83, v217, v93
	v_fmac_f32_e32 v84, v216, v93
	v_fmac_f32_e32 v86, v215, v93
	v_fmac_f32_e32 v87, v214, v93
	v_fmac_f32_e32 v90, v213, v93
	v_fmac_f32_e32 v91, v212, v93
	v_fmac_f32_e32 v94, v211, v93
	v_fmac_f32_e32 v95, v210, v93
	v_fmac_f32_e32 v98, v209, v93
	v_fmac_f32_e32 v99, v208, v93
	v_fmac_f32_e32 v102, v207, v93
	v_fmac_f32_e32 v103, v206, v93
	v_fmac_f32_e32 v106, v205, v93
	s_waitcnt lgkmcnt(0)
	v_fmac_f32_e32 v74, v220, v88
	v_fmac_f32_e32 v75, v219, v88
	v_fmac_f32_e32 v83, v218, v88
	v_fmac_f32_e32 v84, v217, v88
	v_fmac_f32_e32 v86, v216, v88
	v_fmac_f32_e32 v87, v215, v88
	v_fmac_f32_e32 v90, v214, v88
	v_fmac_f32_e32 v91, v213, v88
	v_fmac_f32_e32 v94, v212, v88
	v_fmac_f32_e32 v95, v211, v88
	v_fmac_f32_e32 v98, v210, v88
	v_fmac_f32_e32 v99, v209, v88
	v_fmac_f32_e32 v102, v208, v88
	v_fmac_f32_e32 v103, v207, v88
	v_fmac_f32_e32 v106, v206, v88
	v_fmac_f32_e32 v33, v205, v88
	v_fmac_f32_e32 v74, v221, v89
	v_fmac_f32_e32 v75, v220, v89
	v_fmac_f32_e32 v83, v219, v89
	v_fmac_f32_e32 v84, v218, v89
	v_fmac_f32_e32 v86, v217, v89
	v_fmac_f32_e32 v87, v216, v89
	v_fmac_f32_e32 v90, v215, v89
	v_fmac_f32_e32 v91, v214, v89
	v_fmac_f32_e32 v94, v213, v89
	v_fmac_f32_e32 v95, v212, v89
	v_fmac_f32_e32 v98, v211, v89
	v_fmac_f32_e32 v99, v210, v89
	v_fmac_f32_e32 v102, v209, v89
	v_fmac_f32_e32 v103, v208, v89
	v_fmac_f32_e32 v106, v207, v89
	v_fmac_f32_e32 v33, v206, v89
	ds_read2st64_b32 v[88:89], v40 offset0:56 offset1:58
	s_waitcnt lgkmcnt(0)
; __device__ __forceinline__ void conv_phase(LAS unsigned char* lds, const bf16_t* P, const float* cw, const float* cb, const float* ng, const float* nb, bf16_t* CAT, int bid, int G, const int tid) {
;     ...
;             for (int i = 0; i < 46; ++i) {
;                 const float z = zs[(tb * 16 + i) * 128 + c];
; #pragma unroll
;                 for (int o = 0; o < 16; ++o) { const int j = i - o; if (j >= 0 && j <= 30) acc[o] += wj[j] * z; }
;             }
; #pragma unroll
;             for (int o = 0; o < 16; ++o) co[(tb * 16 + o) * 128 + c] = acc[o];
;         }
;         __syncthreads();
	v_fmac_f32_e32 v33, v207, v88
	v_fmac_f32_e32 v106, v208, v88
	v_fmac_f32_e32 v33, v208, v89
	ds_read2st64_b32 v[80:81], v40 offset0:60 offset1:62
	v_fmac_f32_e32 v103, v209, v88
	v_fmac_f32_e32 v106, v209, v89
	v_fmac_f32_e32 v102, v210, v88
	v_fmac_f32_e32 v103, v210, v89
	s_waitcnt lgkmcnt(0)
	v_fmac_f32_e32 v33, v209, v80
	v_fmac_f32_e32 v106, v210, v80
	v_fmac_f32_e32 v33, v210, v81
	ds_read2st64_b32 v[78:79], v40 offset0:64 offset1:66
	v_fmac_f32_e32 v99, v211, v88
	v_fmac_f32_e32 v102, v211, v89
	v_fmac_f32_e32 v103, v211, v80
	v_fmac_f32_e32 v106, v211, v81
	s_waitcnt lgkmcnt(0)
	v_fmac_f32_e32 v33, v211, v78
	v_fmac_f32_e32 v98, v212, v88
	v_fmac_f32_e32 v99, v212, v89
	v_fmac_f32_e32 v102, v212, v80
	v_fmac_f32_e32 v103, v212, v81
	v_fmac_f32_e32 v106, v212, v78
	v_fmac_f32_e32 v33, v212, v79
	ds_read2st64_b32 v[76:77], v40 offset0:68 offset1:70
	v_fmac_f32_e32 v95, v213, v88
	v_fmac_f32_e32 v98, v213, v89
	v_fmac_f32_e32 v99, v213, v80
	v_fmac_f32_e32 v102, v213, v81
	v_fmac_f32_e32 v103, v213, v78
	v_fmac_f32_e32 v106, v213, v79
	s_waitcnt lgkmcnt(0)
	v_fmac_f32_e32 v33, v213, v76
	v_fmac_f32_e32 v94, v214, v88
	v_fmac_f32_e32 v95, v214, v89
	v_fmac_f32_e32 v98, v214, v80
	v_fmac_f32_e32 v99, v214, v81
	v_fmac_f32_e32 v102, v214, v78
	v_fmac_f32_e32 v103, v214, v79
	v_fmac_f32_e32 v106, v214, v76
	v_fmac_f32_e32 v33, v214, v77
	ds_read2st64_b32 v[72:73], v40 offset0:72 offset1:74
	v_fmac_f32_e32 v91, v215, v88
	v_fmac_f32_e32 v94, v215, v89
	v_fmac_f32_e32 v95, v215, v80
	v_fmac_f32_e32 v98, v215, v81
	v_fmac_f32_e32 v99, v215, v78
	v_fmac_f32_e32 v102, v215, v79
	v_fmac_f32_e32 v103, v215, v76
	v_fmac_f32_e32 v106, v215, v77
	s_waitcnt lgkmcnt(0)
	v_fmac_f32_e32 v33, v215, v72
	v_fmac_f32_e32 v90, v216, v88
	v_fmac_f32_e32 v91, v216, v89
	v_fmac_f32_e32 v94, v216, v80
	v_fmac_f32_e32 v95, v216, v81
	v_fmac_f32_e32 v98, v216, v78
	v_fmac_f32_e32 v99, v216, v79
	v_fmac_f32_e32 v102, v216, v76
	v_fmac_f32_e32 v103, v216, v77
	v_fmac_f32_e32 v106, v216, v72
	v_fmac_f32_e32 v33, v216, v73
	ds_read2st64_b32 v[70:71], v40 offset0:76 offset1:78
	v_fmac_f32_e32 v87, v217, v88
	v_fmac_f32_e32 v90, v217, v89
	v_fmac_f32_e32 v91, v217, v80
	v_fmac_f32_e32 v94, v217, v81
	v_fmac_f32_e32 v95, v217, v78
	v_fmac_f32_e32 v98, v217, v79
	v_fmac_f32_e32 v99, v217, v76
	v_fmac_f32_e32 v102, v217, v77
	v_fmac_f32_e32 v103, v217, v72
	v_fmac_f32_e32 v106, v217, v73
	s_waitcnt lgkmcnt(0)
	v_fmac_f32_e32 v33, v217, v70
	v_fmac_f32_e32 v86, v218, v88
	v_fmac_f32_e32 v87, v218, v89
	v_fmac_f32_e32 v90, v218, v80
	v_fmac_f32_e32 v91, v218, v81
	v_fmac_f32_e32 v94, v218, v78
	v_fmac_f32_e32 v95, v218, v79
	v_fmac_f32_e32 v98, v218, v76
	v_fmac_f32_e32 v99, v218, v77
	v_fmac_f32_e32 v102, v218, v72
	v_fmac_f32_e32 v103, v218, v73
	v_fmac_f32_e32 v106, v218, v70
	v_fmac_f32_e32 v33, v218, v71
	ds_read2st64_b32 v[68:69], v40 offset0:80 offset1:82
	v_fmac_f32_e32 v84, v219, v88
	v_fmac_f32_e32 v86, v219, v89
	v_fmac_f32_e32 v87, v219, v80
	v_fmac_f32_e32 v90, v219, v81
	v_fmac_f32_e32 v91, v219, v78
	v_fmac_f32_e32 v94, v219, v79
	v_fmac_f32_e32 v95, v219, v76
	v_fmac_f32_e32 v98, v219, v77
	v_fmac_f32_e32 v99, v219, v72
	v_fmac_f32_e32 v102, v219, v73
	v_fmac_f32_e32 v103, v219, v70
	v_fmac_f32_e32 v106, v219, v71
	s_waitcnt lgkmcnt(0)
	v_fmac_f32_e32 v33, v219, v68
	v_fmac_f32_e32 v83, v220, v88
	v_fmac_f32_e32 v84, v220, v89
	v_fmac_f32_e32 v86, v220, v80
	v_fmac_f32_e32 v87, v220, v81
	v_fmac_f32_e32 v90, v220, v78
	v_fmac_f32_e32 v91, v220, v79
	v_fmac_f32_e32 v94, v220, v76
	v_fmac_f32_e32 v95, v220, v77
	v_fmac_f32_e32 v98, v220, v72
	v_fmac_f32_e32 v99, v220, v73
	v_fmac_f32_e32 v102, v220, v70
	v_fmac_f32_e32 v103, v220, v71
	v_fmac_f32_e32 v106, v220, v68
	v_fmac_f32_e32 v33, v220, v69
	ds_read2st64_b32 v[66:67], v40 offset0:84 offset1:86
	v_fmac_f32_e32 v75, v221, v88
	v_fmac_f32_e32 v83, v221, v89
	v_fmac_f32_e32 v84, v221, v80
	v_fmac_f32_e32 v86, v221, v81
	v_fmac_f32_e32 v87, v221, v78
	v_fmac_f32_e32 v90, v221, v79
	v_fmac_f32_e32 v91, v221, v76
	v_fmac_f32_e32 v94, v221, v77
	v_fmac_f32_e32 v95, v221, v72
	v_fmac_f32_e32 v98, v221, v73
	v_fmac_f32_e32 v99, v221, v70
	v_fmac_f32_e32 v102, v221, v71
	v_fmac_f32_e32 v103, v221, v68
	v_fmac_f32_e32 v106, v221, v69
	s_waitcnt lgkmcnt(0)
	v_fmac_f32_e32 v33, v221, v66
	v_fmac_f32_e32 v74, v222, v88
	v_fmac_f32_e32 v75, v222, v89
	v_fmac_f32_e32 v83, v222, v80
	v_fmac_f32_e32 v84, v222, v81
	v_fmac_f32_e32 v86, v222, v78
	v_fmac_f32_e32 v87, v222, v79
	v_fmac_f32_e32 v90, v222, v76
	v_fmac_f32_e32 v91, v222, v77
	v_fmac_f32_e32 v94, v222, v72
	v_fmac_f32_e32 v95, v222, v73
	v_fmac_f32_e32 v98, v222, v70
	v_fmac_f32_e32 v99, v222, v71
	v_fmac_f32_e32 v102, v222, v68
	v_fmac_f32_e32 v103, v222, v69
	v_fmac_f32_e32 v106, v222, v66
	v_fmac_f32_e32 v33, v222, v67
	ds_read2st64_b32 v[34:35], v40 offset0:88 offset1:90
	v_fmac_f32_e32 v74, v31, v89
	v_fmac_f32_e32 v75, v31, v80
	v_fmac_f32_e32 v74, v224, v80
	v_fmac_f32_e32 v75, v224, v81
	v_fmac_f32_e32 v83, v31, v81
	v_fmac_f32_e32 v84, v31, v78
	v_fmac_f32_e32 v86, v31, v79
	v_fmac_f32_e32 v87, v31, v76
	v_fmac_f32_e32 v90, v31, v77
	v_fmac_f32_e32 v91, v31, v72
	v_fmac_f32_e32 v94, v31, v73
	v_fmac_f32_e32 v95, v31, v70
	v_fmac_f32_e32 v98, v31, v71
	v_fmac_f32_e32 v99, v31, v68
	v_fmac_f32_e32 v102, v31, v69
	v_fmac_f32_e32 v103, v31, v66
	v_fmac_f32_e32 v106, v31, v67
	s_waitcnt lgkmcnt(0)
	v_fmac_f32_e32 v33, v31, v34
	v_fmac_f32_e32 v83, v224, v78
	v_fmac_f32_e32 v84, v224, v79
	v_fmac_f32_e32 v86, v224, v76
	v_fmac_f32_e32 v87, v224, v77
	v_fmac_f32_e32 v90, v224, v72
	v_fmac_f32_e32 v91, v224, v73
	v_fmac_f32_e32 v94, v224, v70
	v_fmac_f32_e32 v95, v224, v71
	v_fmac_f32_e32 v98, v224, v68
	v_fmac_f32_e32 v99, v224, v69
	v_fmac_f32_e32 v102, v224, v66
	v_fmac_f32_e32 v103, v224, v67
	v_fmac_f32_e32 v106, v224, v34
	v_fmac_f32_e32 v33, v224, v35
	ds_write2st64_b32 v40, v74, v75 offset0:188 offset1:190
	ds_write2st64_b32 v40, v83, v84 offset0:192 offset1:194
	ds_write2st64_b32 v40, v86, v87 offset0:196 offset1:198
	ds_write2st64_b32 v40, v90, v91 offset0:200 offset1:202
	ds_write2st64_b32 v40, v94, v95 offset0:204 offset1:206
	ds_write2st64_b32 v40, v98, v99 offset0:208 offset1:210
	ds_write2st64_b32 v40, v102, v103 offset0:212 offset1:214
	ds_write2st64_b32 v40, v106, v33 offset0:216 offset1:218
	s_waitcnt lgkmcnt(0)
	s_barrier
; #define LAS __attribute__((address_space(3)))
; __device__ __forceinline__ void conv_phase(LAS unsigned char* lds, const bf16_t* P, const float* cw, const float* cb, const float* ng, const float* nb, bf16_t* CAT, int bid, int G, const int tid) {
;     ...
;             const f32x2 gg = *(const f32x2*)(ng + g * 128 + 2 * lane), bb = *(const f32x2*)(nb + g * 128 + 2 * lane);
; #pragma unroll
;             for (int k = 0; k < 8; ++k) {
;                 const int tok = w * 8 + k;
;                 const f32x2 v = *(const LAS f32x2*)(co + tok * 128 + 2 * lane);
;                 const float mean = wave_sum(v[0] + v[1]) * (1.0f / 128.0f);
;                 const float d0 = v[0] - mean, d1 = v[1] - mean;
;                 const float rs = __builtin_amdgcn_rsqf(wave_sum(d0 * d0 + d1 * d1) * (1.0f / 128.0f) + EPS);
	s_lshl_b32 s26, s30, 1
	v_mov_b32_e32 v31, v177
	ds_read_b64 v[110:111], v58 offset:48128
	ds_read_b64 v[112:113], v59 offset:48128
	ds_read_b64 v[114:115], v60 offset:48128
	ds_read_b64 v[116:117], v61 offset:48128
	ds_read_b64 v[118:119], v62 offset:48128
	ds_read_b64 v[120:121], v63 offset:48128
	ds_read_b64 v[122:123], v64 offset:48128
	ds_read_b64 v[124:125], v65 offset:48128
	s_waitcnt lgkmcnt(7)
	v_add_f32_e32 v126, v110, v111
	s_waitcnt lgkmcnt(6)
	v_add_f32_e32 v127, v112, v113
	s_waitcnt lgkmcnt(5)
	v_add_f32_e32 v128, v114, v115
	s_waitcnt lgkmcnt(4)
	v_add_f32_e32 v129, v116, v117
	s_waitcnt lgkmcnt(3)
	v_add_f32_e32 v130, v118, v119
	s_waitcnt lgkmcnt(2)
	v_add_f32_e32 v131, v120, v121
	s_waitcnt lgkmcnt(1)
	v_add_f32_e32 v132, v122, v123
	s_waitcnt lgkmcnt(0)
	v_add_f32_e32 v133, v124, v125
	v_add_f32_dpp v126, v126, v126 quad_perm:[1,0,3,2] row_mask:0xf bank_mask:0xf
	v_add_f32_dpp v127, v127, v127 quad_perm:[1,0,3,2] row_mask:0xf bank_mask:0xf
	v_add_f32_dpp v128, v128, v128 quad_perm:[1,0,3,2] row_mask:0xf bank_mask:0xf
	v_add_f32_dpp v129, v129, v129 quad_perm:[1,0,3,2] row_mask:0xf bank_mask:0xf
	v_add_f32_dpp v130, v130, v130 quad_perm:[1,0,3,2] row_mask:0xf bank_mask:0xf
	v_add_f32_dpp v131, v131, v131 quad_perm:[1,0,3,2] row_mask:0xf bank_mask:0xf
	v_add_f32_dpp v132, v132, v132 quad_perm:[1,0,3,2] row_mask:0xf bank_mask:0xf
	v_add_f32_dpp v133, v133, v133 quad_perm:[1,0,3,2] row_mask:0xf bank_mask:0xf
	v_add_f32_dpp v126, v126, v126 quad_perm:[2,3,0,1] row_mask:0xf bank_mask:0xf
	v_add_f32_dpp v127, v127, v127 quad_perm:[2,3,0,1] row_mask:0xf bank_mask:0xf
	v_add_f32_dpp v128, v128, v128 quad_perm:[2,3,0,1] row_mask:0xf bank_mask:0xf
	v_add_f32_dpp v129, v129, v129 quad_perm:[2,3,0,1] row_mask:0xf bank_mask:0xf
	v_add_f32_dpp v130, v130, v130 quad_perm:[2,3,0,1] row_mask:0xf bank_mask:0xf
	v_add_f32_dpp v131, v131, v131 quad_perm:[2,3,0,1] row_mask:0xf bank_mask:0xf
	v_add_f32_dpp v132, v132, v132 quad_perm:[2,3,0,1] row_mask:0xf bank_mask:0xf
	v_add_f32_dpp v133, v133, v133 quad_perm:[2,3,0,1] row_mask:0xf bank_mask:0xf
	v_add_f32_dpp v126, v126, v126 row_half_mirror row_mask:0xf bank_mask:0xf
	v_add_f32_dpp v127, v127, v127 row_half_mirror row_mask:0xf bank_mask:0xf
	v_add_f32_dpp v128, v128, v128 row_half_mirror row_mask:0xf bank_mask:0xf
	v_add_f32_dpp v129, v129, v129 row_half_mirror row_mask:0xf bank_mask:0xf
	v_add_f32_dpp v130, v130, v130 row_half_mirror row_mask:0xf bank_mask:0xf
	v_add_f32_dpp v131, v131, v131 row_half_mirror row_mask:0xf bank_mask:0xf
	v_add_f32_dpp v132, v132, v132 row_half_mirror row_mask:0xf bank_mask:0xf
	v_add_f32_dpp v133, v133, v133 row_half_mirror row_mask:0xf bank_mask:0xf
	v_add_f32_dpp v126, v126, v126 row_mirror row_mask:0xf bank_mask:0xf
	v_add_f32_dpp v127, v127, v127 row_mirror row_mask:0xf bank_mask:0xf
	v_add_f32_dpp v128, v128, v128 row_mirror row_mask:0xf bank_mask:0xf
	v_add_f32_dpp v129, v129, v129 row_mirror row_mask:0xf bank_mask:0xf
	v_add_f32_dpp v130, v130, v130 row_mirror row_mask:0xf bank_mask:0xf
	v_add_f32_dpp v131, v131, v131 row_mirror row_mask:0xf bank_mask:0xf
	v_add_f32_dpp v132, v132, v132 row_mirror row_mask:0xf bank_mask:0xf
	v_add_f32_dpp v133, v133, v133 row_mirror row_mask:0xf bank_mask:0xf
	v_mov_b32_e32 v134, v126
	v_mov_b32_e32 v135, v127
	v_mov_b32_e32 v136, v128
	v_mov_b32_e32 v137, v129
	v_mov_b32_e32 v138, v130
	v_mov_b32_e32 v139, v131
	v_mov_b32_e32 v140, v132
	v_mov_b32_e32 v141, v133
	v_permlane16_swap_b32 v126, v134
	v_permlane16_swap_b32 v127, v135
	v_permlane16_swap_b32 v128, v136
	v_permlane16_swap_b32 v129, v137
	v_permlane16_swap_b32 v130, v138
	v_permlane16_swap_b32 v131, v139
	v_permlane16_swap_b32 v132, v140
	v_permlane16_swap_b32 v133, v141
	v_add_f32_e32 v126, v126, v134
	v_add_f32_e32 v127, v127, v135
	v_add_f32_e32 v128, v128, v136
	v_add_f32_e32 v129, v129, v137
	v_add_f32_e32 v130, v130, v138
	v_add_f32_e32 v131, v131, v139
	v_add_f32_e32 v132, v132, v140
	v_add_f32_e32 v133, v133, v141
	v_mov_b32_e32 v134, v126
	v_mov_b32_e32 v135, v127
	v_mov_b32_e32 v136, v128
	v_mov_b32_e32 v137, v129
	v_mov_b32_e32 v138, v130
	v_mov_b32_e32 v139, v131
	v_mov_b32_e32 v140, v132
	v_mov_b32_e32 v141, v133
	v_permlane32_swap_b32 v126, v134
	v_permlane32_swap_b32 v127, v135
	v_permlane32_swap_b32 v128, v136
	v_permlane32_swap_b32 v129, v137
	v_permlane32_swap_b32 v130, v138
	v_permlane32_swap_b32 v131, v139
	v_permlane32_swap_b32 v132, v140
	v_permlane32_swap_b32 v133, v141
	v_add_f32_e32 v126, v126, v134
	v_add_f32_e32 v127, v127, v135
	v_add_f32_e32 v128, v128, v136
	v_add_f32_e32 v129, v129, v137
	v_add_f32_e32 v130, v130, v138
	v_add_f32_e32 v131, v131, v139
	v_add_f32_e32 v132, v132, v140
	v_add_f32_e32 v133, v133, v141
	v_fmac_f32_e32 v111, 0xbc000000, v126
	v_fmamk_f32 v110, v126, 0xbc000000, v110
	v_fmac_f32_e32 v113, 0xbc000000, v127
	v_fmamk_f32 v112, v127, 0xbc000000, v112
	v_fmac_f32_e32 v115, 0xbc000000, v128
	v_fmamk_f32 v114, v128, 0xbc000000, v114
	v_fmac_f32_e32 v117, 0xbc000000, v129
	v_fmamk_f32 v116, v129, 0xbc000000, v116
	v_fmac_f32_e32 v119, 0xbc000000, v130
	v_fmamk_f32 v118, v130, 0xbc000000, v118
	v_fmac_f32_e32 v121, 0xbc000000, v131
	v_fmamk_f32 v120, v131, 0xbc000000, v120
	v_fmac_f32_e32 v123, 0xbc000000, v132
	v_fmamk_f32 v122, v132, 0xbc000000, v122
	v_fmac_f32_e32 v125, 0xbc000000, v133
	v_fmamk_f32 v124, v133, 0xbc000000, v124
	v_mul_f32_e32 v126, v111, v111
	v_fmac_f32_e32 v126, v110, v110
	v_mul_f32_e32 v127, v113, v113
	v_fmac_f32_e32 v127, v112, v112
	v_mul_f32_e32 v128, v115, v115
	v_fmac_f32_e32 v128, v114, v114
	v_mul_f32_e32 v129, v117, v117
	v_fmac_f32_e32 v129, v116, v116
	v_mul_f32_e32 v130, v119, v119
; __device__ __forceinline__ void conv_phase(LAS unsigned char* lds, const bf16_t* P, const float* cw, const float* cb, const float* ng, const float* nb, bf16_t* CAT, int bid, int G, const int tid) {
;     ...
;                 const float mean = wave_sum(v[0] + v[1]) * (1.0f / 128.0f);
;                 const float d0 = v[0] - mean, d1 = v[1] - mean;
;                 const float rs = __builtin_amdgcn_rsqf(wave_sum(d0 * d0 + d1 * d1) * (1.0f / 128.0f) + EPS);
	v_fmac_f32_e32 v130, v118, v118
	v_mul_f32_e32 v131, v121, v121
	v_fmac_f32_e32 v131, v120, v120
	v_mul_f32_e32 v132, v123, v123
	v_fmac_f32_e32 v132, v122, v122
	v_mul_f32_e32 v133, v125, v125
	v_fmac_f32_e32 v133, v124, v124
	v_add_f32_dpp v126, v126, v126 quad_perm:[1,0,3,2] row_mask:0xf bank_mask:0xf
	v_add_f32_dpp v127, v127, v127 quad_perm:[1,0,3,2] row_mask:0xf bank_mask:0xf
	v_add_f32_dpp v128, v128, v128 quad_perm:[1,0,3,2] row_mask:0xf bank_mask:0xf
	v_add_f32_dpp v129, v129, v129 quad_perm:[1,0,3,2] row_mask:0xf bank_mask:0xf
	v_add_f32_dpp v130, v130, v130 quad_perm:[1,0,3,2] row_mask:0xf bank_mask:0xf
	v_add_f32_dpp v131, v131, v131 quad_perm:[1,0,3,2] row_mask:0xf bank_mask:0xf
	v_add_f32_dpp v132, v132, v132 quad_perm:[1,0,3,2] row_mask:0xf bank_mask:0xf
	v_add_f32_dpp v133, v133, v133 quad_perm:[1,0,3,2] row_mask:0xf bank_mask:0xf
	v_add_f32_dpp v126, v126, v126 quad_perm:[2,3,0,1] row_mask:0xf bank_mask:0xf
	v_add_f32_dpp v127, v127, v127 quad_perm:[2,3,0,1] row_mask:0xf bank_mask:0xf
	v_add_f32_dpp v128, v128, v128 quad_perm:[2,3,0,1] row_mask:0xf bank_mask:0xf
	v_add_f32_dpp v129, v129, v129 quad_perm:[2,3,0,1] row_mask:0xf bank_mask:0xf
	v_add_f32_dpp v130, v130, v130 quad_perm:[2,3,0,1] row_mask:0xf bank_mask:0xf
	v_add_f32_dpp v131, v131, v131 quad_perm:[2,3,0,1] row_mask:0xf bank_mask:0xf
	v_add_f32_dpp v132, v132, v132 quad_perm:[2,3,0,1] row_mask:0xf bank_mask:0xf
	v_add_f32_dpp v133, v133, v133 quad_perm:[2,3,0,1] row_mask:0xf bank_mask:0xf
	v_add_f32_dpp v126, v126, v126 row_half_mirror row_mask:0xf bank_mask:0xf
	v_add_f32_dpp v127, v127, v127 row_half_mirror row_mask:0xf bank_mask:0xf
	v_add_f32_dpp v128, v128, v128 row_half_mirror row_mask:0xf bank_mask:0xf
	v_add_f32_dpp v129, v129, v129 row_half_mirror row_mask:0xf bank_mask:0xf
	v_add_f32_dpp v130, v130, v130 row_half_mirror row_mask:0xf bank_mask:0xf
	v_add_f32_dpp v131, v131, v131 row_half_mirror row_mask:0xf bank_mask:0xf
	v_add_f32_dpp v132, v132, v132 row_half_mirror row_mask:0xf bank_mask:0xf
	v_add_f32_dpp v133, v133, v133 row_half_mirror row_mask:0xf bank_mask:0xf
	v_add_f32_dpp v126, v126, v126 row_mirror row_mask:0xf bank_mask:0xf
	v_add_f32_dpp v127, v127, v127 row_mirror row_mask:0xf bank_mask:0xf
	v_add_f32_dpp v128, v128, v128 row_mirror row_mask:0xf bank_mask:0xf
	v_add_f32_dpp v129, v129, v129 row_mirror row_mask:0xf bank_mask:0xf
	v_add_f32_dpp v130, v130, v130 row_mirror row_mask:0xf bank_mask:0xf
	v_add_f32_dpp v131, v131, v131 row_mirror row_mask:0xf bank_mask:0xf
	v_add_f32_dpp v132, v132, v132 row_mirror row_mask:0xf bank_mask:0xf
	v_add_f32_dpp v133, v133, v133 row_mirror row_mask:0xf bank_mask:0xf
	v_mov_b32_e32 v134, v126
	v_mov_b32_e32 v135, v127
	v_mov_b32_e32 v136, v128
	v_mov_b32_e32 v137, v129
	v_mov_b32_e32 v138, v130
	v_mov_b32_e32 v139, v131
	v_mov_b32_e32 v140, v132
	v_mov_b32_e32 v141, v133
	v_permlane16_swap_b32 v126, v134
	v_permlane16_swap_b32 v127, v135
	v_permlane16_swap_b32 v128, v136
	v_permlane16_swap_b32 v129, v137
	v_permlane16_swap_b32 v130, v138
	v_permlane16_swap_b32 v131, v139
	v_permlane16_swap_b32 v132, v140
	v_permlane16_swap_b32 v133, v141
	v_add_f32_e32 v126, v126, v134
	v_add_f32_e32 v127, v127, v135
	v_add_f32_e32 v128, v128, v136
	v_add_f32_e32 v129, v129, v137
	v_add_f32_e32 v130, v130, v138
	v_add_f32_e32 v131, v131, v139
	v_add_f32_e32 v132, v132, v140
	v_add_f32_e32 v133, v133, v141
	v_mov_b32_e32 v134, v126
	v_mov_b32_e32 v135, v127
	v_mov_b32_e32 v136, v128
	v_mov_b32_e32 v137, v129
	v_mov_b32_e32 v138, v130
	v_mov_b32_e32 v139, v131
	v_mov_b32_e32 v140, v132
	v_mov_b32_e32 v141, v133
	v_permlane32_swap_b32 v126, v134
	v_permlane32_swap_b32 v127, v135
	v_permlane32_swap_b32 v128, v136
	v_permlane32_swap_b32 v129, v137
	v_permlane32_swap_b32 v130, v138
	v_permlane32_swap_b32 v131, v139
	v_permlane32_swap_b32 v132, v140
	v_permlane32_swap_b32 v133, v141
	v_add_f32_e32 v126, v126, v134
	v_add_f32_e32 v127, v127, v135
	v_add_f32_e32 v128, v128, v136
	v_add_f32_e32 v129, v129, v137
	v_add_f32_e32 v130, v130, v138
	v_add_f32_e32 v131, v131, v139
	v_add_f32_e32 v132, v132, v140
	v_add_f32_e32 v133, v133, v141
	v_fmamk_f32 v126, v126, 0x3c000000, v189
	v_fmamk_f32 v127, v127, 0x3c000000, v189
	v_fmamk_f32 v128, v128, 0x3c000000, v189
	v_fmamk_f32 v129, v129, 0x3c000000, v189
	v_fmamk_f32 v130, v130, 0x3c000000, v189
	v_fmamk_f32 v131, v131, 0x3c000000, v189
	v_fmamk_f32 v132, v132, 0x3c000000, v189
	v_fmamk_f32 v133, v133, 0x3c000000, v189
	v_rsq_f32_e32 v126, v126
	v_rsq_f32_e32 v127, v127
	v_rsq_f32_e32 v128, v128
	v_rsq_f32_e32 v129, v129
	v_rsq_f32_e32 v130, v130
	v_rsq_f32_e32 v131, v131
	v_rsq_f32_e32 v132, v132
	v_rsq_f32_e32 v133, v133
	v_mul_f32_e32 v110, v110, v126
	v_mul_f32_e32 v111, v111, v126
	v_mul_f32_e32 v112, v112, v127
; __device__ __forceinline__ unsigned cvt_pk_bf16(float lo, float hi) { unsigned r; asm("v_cvt_pk_bf16_f32 %0, %1, %2" : "=v"(r) : "v"(lo), "v"(hi)); return r; }
; __device__ __forceinline__ float silu_f(float x) { return x * fast_sigmoid(x); }
; __device__ __forceinline__ void conv_phase(LAS unsigned char* lds, const bf16_t* P, const float* cw, const float* cb, const float* ng, const float* nb, bf16_t* CAT, int bid, int G, const int tid) {
;     ...
;                 const float rs = __builtin_amdgcn_rsqf(wave_sum(d0 * d0 + d1 * d1) * (1.0f / 128.0f) + EPS);
;                 const float y0 = d0 * rs * gg[0] + bb[0], y1 = d1 * rs * gg[1] + bb[1];
;                 *(unsigned*)(CAT + (size_t)(b * SEQ + t0 + tok) * D + 1024 + g * 128 + 2 * lane) = cvt_pk_bf16(silu_f(y0), silu_f(y1));
	v_mul_f32_e32 v113, v113, v127
	v_mul_f32_e32 v114, v114, v128
	v_mul_f32_e32 v115, v115, v128
	v_mul_f32_e32 v116, v116, v129
	v_mul_f32_e32 v117, v117, v129
	v_mul_f32_e32 v118, v118, v130
	v_mul_f32_e32 v119, v119, v130
	v_mul_f32_e32 v120, v120, v131
	v_mul_f32_e32 v121, v121, v131
	v_mul_f32_e32 v122, v122, v132
	v_mul_f32_e32 v123, v123, v132
	v_mul_f32_e32 v124, v124, v133
	v_mul_f32_e32 v125, v125, v133
	v_fma_f32 v110, v150, v110, v152
	v_fma_f32 v111, v151, v111, v153
	v_fma_f32 v112, v150, v112, v152
	v_fma_f32 v113, v151, v113, v153
	v_fma_f32 v114, v150, v114, v152
	v_fma_f32 v115, v151, v115, v153
	v_fma_f32 v116, v150, v116, v152
	v_fma_f32 v117, v151, v117, v153
	v_fma_f32 v118, v150, v118, v152
	v_fma_f32 v119, v151, v119, v153
	v_fma_f32 v120, v150, v120, v152
	v_fma_f32 v121, v151, v121, v153
	v_fma_f32 v122, v150, v122, v152
	v_fma_f32 v123, v151, v123, v153
	v_fma_f32 v124, v150, v124, v152
	v_fma_f32 v125, v151, v125, v153
	v_mul_f32_e32 v134, 0xbfb8aa3b, v110
	v_mul_f32_e32 v142, 0xbfb8aa3b, v111
	v_mul_f32_e32 v135, 0xbfb8aa3b, v112
	v_mul_f32_e32 v143, 0xbfb8aa3b, v113
	v_mul_f32_e32 v136, 0xbfb8aa3b, v114
	v_mul_f32_e32 v144, 0xbfb8aa3b, v115
	v_mul_f32_e32 v137, 0xbfb8aa3b, v116
	v_mul_f32_e32 v145, 0xbfb8aa3b, v117
	v_mul_f32_e32 v138, 0xbfb8aa3b, v118
	v_mul_f32_e32 v146, 0xbfb8aa3b, v119
	v_mul_f32_e32 v139, 0xbfb8aa3b, v120
	v_mul_f32_e32 v147, 0xbfb8aa3b, v121
	v_mul_f32_e32 v140, 0xbfb8aa3b, v122
	v_mul_f32_e32 v148, 0xbfb8aa3b, v123
	v_mul_f32_e32 v141, 0xbfb8aa3b, v124
	v_mul_f32_e32 v149, 0xbfb8aa3b, v125
	v_exp_f32_e32 v134, v134
	v_exp_f32_e32 v142, v142
	v_exp_f32_e32 v135, v135
	v_exp_f32_e32 v143, v143
	v_exp_f32_e32 v136, v136
	v_exp_f32_e32 v144, v144
	v_exp_f32_e32 v137, v137
	v_exp_f32_e32 v145, v145
	v_exp_f32_e32 v138, v138
	v_exp_f32_e32 v146, v146
	v_exp_f32_e32 v139, v139
	v_exp_f32_e32 v147, v147
	v_exp_f32_e32 v140, v140
	v_exp_f32_e32 v148, v148
	v_exp_f32_e32 v141, v141
	v_exp_f32_e32 v149, v149
	s_nop 0
	v_add_f32_e32 v134, 1.0, v134
	v_add_f32_e32 v142, 1.0, v142
	v_add_f32_e32 v135, 1.0, v135
	v_add_f32_e32 v143, 1.0, v143
	v_add_f32_e32 v136, 1.0, v136
	v_add_f32_e32 v144, 1.0, v144
	v_add_f32_e32 v137, 1.0, v137
	v_add_f32_e32 v145, 1.0, v145
	v_add_f32_e32 v138, 1.0, v138
	v_add_f32_e32 v146, 1.0, v146
	v_add_f32_e32 v139, 1.0, v139
	v_add_f32_e32 v147, 1.0, v147
	v_add_f32_e32 v140, 1.0, v140
	v_add_f32_e32 v148, 1.0, v148
	v_add_f32_e32 v141, 1.0, v141
	v_add_f32_e32 v149, 1.0, v149
	v_rcp_f32_e32 v134, v134
	v_rcp_f32_e32 v142, v142
	v_rcp_f32_e32 v135, v135
	v_rcp_f32_e32 v143, v143
	v_rcp_f32_e32 v136, v136
	v_rcp_f32_e32 v144, v144
	v_rcp_f32_e32 v137, v137
	v_rcp_f32_e32 v145, v145
	v_rcp_f32_e32 v138, v138
	v_rcp_f32_e32 v146, v146
	v_rcp_f32_e32 v139, v139
	v_rcp_f32_e32 v147, v147
	v_rcp_f32_e32 v140, v140
	v_rcp_f32_e32 v148, v148
	v_rcp_f32_e32 v141, v141
	v_rcp_f32_e32 v149, v149
	s_nop 0
	v_mul_f32_e32 v110, v110, v134
	v_mul_f32_e32 v111, v111, v142
	v_mul_f32_e32 v112, v112, v135
	v_mul_f32_e32 v113, v113, v143
	v_mul_f32_e32 v114, v114, v136
	v_mul_f32_e32 v115, v115, v144
	v_mul_f32_e32 v116, v116, v137
	v_mul_f32_e32 v117, v117, v145
	v_mul_f32_e32 v118, v118, v138
	v_mul_f32_e32 v119, v119, v146
	v_mul_f32_e32 v120, v120, v139
	v_mul_f32_e32 v121, v121, v147
	v_mul_f32_e32 v122, v122, v140
	v_mul_f32_e32 v123, v123, v148
	v_mul_f32_e32 v124, v124, v141
	v_mul_f32_e32 v125, v125, v149
	v_cvt_pk_bf16_f32 v134, v110, v111
	v_cvt_pk_bf16_f32 v135, v112, v113
	v_cvt_pk_bf16_f32 v136, v114, v115
	v_cvt_pk_bf16_f32 v137, v116, v117
	v_cvt_pk_bf16_f32 v138, v118, v119
	v_cvt_pk_bf16_f32 v139, v120, v121
	v_cvt_pk_bf16_f32 v140, v122, v123
	v_cvt_pk_bf16_f32 v141, v124, v125
	s_mov_b64 s[64:65], 0x1000
	v_add_u32_e32 v66, s31, v41
	v_ashrrev_i32_e32 v67, 31, v66
	v_lshlrev_b64 v[66:67], 12, v[66:67]
	v_lshl_add_u64 v[66:67], s[92:93], 0, v[66:67]
	v_lshl_add_u64 v[66:67], v[66:67], 0, s[26:27]
	v_lshl_add_u64 v[66:67], v[66:67], 0, v[30:31]
	global_store_dword v[66:67], v134, off offset:2048
	v_lshl_add_u64 v[66:67], v[66:67], 0, s[64:65]
	global_store_dword v[66:67], v135, off offset:2048
	v_lshl_add_u64 v[66:67], v[66:67], 0, s[64:65]
	global_store_dword v[66:67], v136, off offset:2048
	v_lshl_add_u64 v[66:67], v[66:67], 0, s[64:65]
	global_store_dword v[66:67], v137, off offset:2048
	v_lshl_add_u64 v[66:67], v[66:67], 0, s[64:65]
	global_store_dword v[66:67], v138, off offset:2048
	v_lshl_add_u64 v[66:67], v[66:67], 0, s[64:65]
	global_store_dword v[66:67], v139, off offset:2048
	v_lshl_add_u64 v[66:67], v[66:67], 0, s[64:65]
	global_store_dword v[66:67], v140, off offset:2048
	v_lshl_add_u64 v[66:67], v[66:67], 0, s[64:65]
	global_store_dword v[66:67], v141, off offset:2048
	s_cbranch_vccz .LBB0_186
